# static s_setprio 1 for waves 4-7 (younger half) at kernel entry, on top of gemm_wide store weave
# speedup vs baseline: 1.0169x; 1.0169x over previous
; #define LAS __attribute__((address_space(3)))
; __device__ __forceinline__ int half_id() { return __builtin_amdgcn_readfirstlane((int)(threadIdx.x >> 8)); }
; __global__ void __launch_bounds__(512, 2) fwd_megakernel(Params p) {
;   cg::grid_group grid = cg::this_grid();
;   if (p.inv_freq[0] < 0.f) grid.sync();
;   volatile LAS unsigned* xst = (volatile LAS unsigned*)(smem_all + 2 * SMEM_BYTES);
;   if (threadIdx.x == 0) { xst[0] = 0u; xst[1] = 0u; xst[2] = 0u; xst[3] = 0u; }
;   __syncthreads();
_Z14fwd_megakernel6Params:
	v_readfirstlane_b32 s3, v0
	s_nop 3
	s_and_b32 s3, s3, 0x3ff
	s_lshr_b32 s3, s3, 8
	s_cmp_eq_u32 s3, 0
	s_cbranch_scc1 .Lprio_done
	s_setprio 1
.Lprio_done:
	s_load_dword s3, s[0:1], 0xd0
	s_add_u32 s28, s0, 0x110
	s_addc_u32 s29, s1, 0
	s_waitcnt lgkmcnt(0)
	v_cmp_lt_f32_e64 s[4:5], s3, 0
	s_and_b64 vcc, exec, s[4:5]
	s_cbranch_vccnz .LBB0_2
	v_and_b32_e32 v175, 0x3ff, v0
	s_load_dword s33, s[0:1], 0x118
	s_cbranch_execz .LBB0_3
	s_branch .LBB0_14
